# hand-scheduled F epilogue + attention step-1 QK MFMA hoisted before its VALU group + gMLP units moved off the 16 WGs that own a context-attention unit
# speedup vs baseline: 1.0109x; 1.0057x over previous
.LBB0_923:
	s_mov_b32 s0, s25
	s_mov_b32 s1, s7
	s_mov_b32 s6, s24
	v_add_u32_e32 v51, s18, v243
	ds_read_b64_tr_b16 v[52:53], v51 offset:24576
	ds_read_b64_tr_b16 v[54:55], v51 offset:25088
	s_waitcnt lgkmcnt(9)
	v_mfma_f32_32x32x16_bf16 v[114:129], v[194:197], v[150:153], v[2:17]
	v_add_f32_e32 v60, v82, v83
	v_add_f32_e32 v60, v84, v60
	v_add_f32_e32 v60, v85, v60
	v_add_f32_e32 v60, v86, v60
	v_add_f32_e32 v64, v87, v60
	v_cvt_pk_bf16_f32 v162, v82, v83
	v_cvt_pk_bf16_f32 v163, v84, v85
	ds_read_b64_tr_b16 v[60:61], v51 offset:28672
	ds_read_b64_tr_b16 v[62:63], v51 offset:29184
	s_waitcnt lgkmcnt(10)
	v_mfma_f32_32x32x16_bf16 v[98:113], v[190:193], v[150:153], v[2:17]
	v_add_f32_e32 v64, v88, v64
	v_add_f32_e32 v64, v89, v64
	v_add_f32_e32 v64, v90, v64
	v_add_f32_e32 v64, v91, v64
	v_cvt_pk_bf16_f32 v164, v86, v87
	v_cvt_pk_bf16_f32 v165, v88, v89
	ds_read_b64_tr_b16 v[82:83], v51 offset:25600
	ds_read_b64_tr_b16 v[84:85], v51 offset:26112
	s_waitcnt lgkmcnt(11)
	v_mfma_f32_32x32x16_bf16 v[114:129], v[186:189], v[142:145], v[114:129]
	v_add_f32_e32 v64, v92, v64
	v_add_f32_e32 v64, v93, v64
	v_add_f32_e32 v64, v94, v64
	v_add_f32_e32 v64, v95, v64
	v_cvt_pk_bf16_f32 v158, v90, v91
	v_cvt_pk_bf16_f32 v159, v92, v93
	ds_read_b64_tr_b16 v[86:87], v51 offset:29696
	ds_read_b64_tr_b16 v[88:89], v51 offset:30208
	s_waitcnt lgkmcnt(12)
	v_mfma_f32_32x32x16_bf16 v[98:113], v[182:185], v[142:145], v[98:113]
	v_add_f32_e32 v64, v96, v64
	v_add_f32_e32 v64, v97, v64
	v_add_f32_e32 v64, v66, v64
	v_add_f32_e32 v64, v67, v64
	v_cvt_pk_bf16_f32 v160, v94, v95
	v_cvt_pk_bf16_f32 v161, v96, v97
	ds_read_b64_tr_b16 v[90:91], v51 offset:26624
	ds_read_b64_tr_b16 v[92:93], v51 offset:27136
	s_waitcnt lgkmcnt(13)
	v_mfma_f32_32x32x16_bf16 v[114:129], v[178:181], v[138:141], v[114:129]
	v_add_f32_e32 v64, v68, v64
	v_add_f32_e32 v64, v69, v64
	v_add_f32_e32 v64, v70, v64
	v_add_f32_e32 v94, v71, v64
	v_cvt_pk_bf16_f32 v154, v66, v67
	v_cvt_pk_bf16_f32 v155, v68, v69
	ds_read_b64_tr_b16 v[64:65], v51 offset:30720
	ds_read_b64_tr_b16 v[66:67], v51 offset:31232
	s_waitcnt lgkmcnt(14)
	v_mfma_f32_32x32x16_bf16 v[98:113], v[174:177], v[138:141], v[98:113]
	v_add_f32_e32 v68, v72, v94
	v_add_f32_e32 v68, v73, v68
	v_add_f32_e32 v68, v74, v68
	v_add_f32_e32 v94, v75, v68
	v_cvt_pk_bf16_f32 v156, v70, v71
	v_cvt_pk_bf16_f32 v157, v72, v73
	ds_read_b64_tr_b16 v[68:69], v51 offset:27648
	ds_read_b64_tr_b16 v[70:71], v51 offset:28160
	s_waitcnt lgkmcnt(14)
	v_mfma_f32_32x32x16_bf16 v[114:129], v[170:173], v[134:137], v[114:129]
	v_add_f32_e32 v72, v76, v94
	v_add_f32_e32 v72, v77, v72
	v_add_f32_e32 v72, v78, v72
	v_add_f32_e32 v94, v79, v72
	v_cvt_pk_bf16_f32 v146, v74, v75
	v_cvt_pk_bf16_f32 v147, v76, v77
	ds_read_b64_tr_b16 v[72:73], v51 offset:31744
	ds_read_b64_tr_b16 v[74:75], v51 offset:32256
	v_mfma_f32_32x32x16_bf16 v[98:113], v[166:169], v[134:137], v[98:113]
	v_add_f32_e32 v51, v80, v94
	v_add_f32_e32 v51, v81, v51
	v_add_f32_e32 v51, 0, v51
	v_cvt_pk_bf16_f32 v148, v78, v79
	v_cvt_pk_bf16_f32 v149, v80, v81
	v_lshl_add_u64 v[76:77], v[58:59], 0, s[74:75]
	s_add_i32 s7, s24, s22
	s_mov_b32 s18, m0
	s_mov_b32 m0, s7
	s_nop 0
	global_load_lds_dwordx4 v[76:77], off
	s_mov_b32 m0, s18
	v_lshl_add_u64 v[76:77], v[56:57], 0, s[74:75]
	s_add_i32 s7, s25, s23
	s_mov_b32 s18, m0
	s_mov_b32 m0, s7
	s_nop 0
	global_load_lds_dwordx4 v[76:77], off
	s_mov_b32 m0, s18
	s_waitcnt lgkmcnt(14)
	v_mfma_f32_32x32x16_bf16 v[18:33], v[162:165], v[52:55], v[18:33]
	v_exp_f32_e32 v114, v114
	v_exp_f32_e32 v115, v115
	v_exp_f32_e32 v116, v116
	v_exp_f32_e32 v117, v117
	s_waitcnt lgkmcnt(12)
	v_mfma_f32_32x32x16_bf16 v[34:49], v[162:165], v[60:63], v[34:49]
	v_exp_f32_e32 v118, v118
	v_exp_f32_e32 v119, v119
	v_exp_f32_e32 v120, v120
	v_exp_f32_e32 v121, v121
	v_add_u32_e32 v52, s0, v240
	ds_read_b128 v[60:63], v52
	ds_read_b128 v[166:169], v52 offset:512
	s_waitcnt lgkmcnt(12)
	v_mfma_f32_32x32x16_bf16 v[18:33], v[158:161], v[82:85], v[18:33]
	v_exp_f32_e32 v122, v122
	v_exp_f32_e32 v123, v123
	v_exp_f32_e32 v124, v124
	v_exp_f32_e32 v125, v125
	ds_read_b128 v[170:173], v52 offset:2048
	ds_read_b128 v[174:177], v52 offset:2560
	s_waitcnt lgkmcnt(12)
	v_mfma_f32_32x32x16_bf16 v[34:49], v[158:161], v[86:89], v[34:49]
	v_exp_f32_e32 v126, v126
	v_exp_f32_e32 v127, v127
	v_exp_f32_e32 v128, v128
	v_exp_f32_e32 v129, v129
	ds_read_b128 v[178:181], v52 offset:4096
	ds_read_b128 v[182:185], v52 offset:4608
	s_waitcnt lgkmcnt(12)
	v_mfma_f32_32x32x16_bf16 v[18:33], v[154:157], v[90:93], v[18:33]
	v_exp_f32_e32 v98, v98
	v_exp_f32_e32 v99, v99
	v_exp_f32_e32 v100, v100
	v_exp_f32_e32 v101, v101
	ds_read_b128 v[186:189], v52 offset:6144
	ds_read_b128 v[52:55], v52 offset:6656
	s_waitcnt lgkmcnt(12)
	v_mfma_f32_32x32x16_bf16 v[34:49], v[154:157], v[64:67], v[34:49]
	v_exp_f32_e32 v102, v102
	v_exp_f32_e32 v103, v103
	v_exp_f32_e32 v104, v104
	v_exp_f32_e32 v105, v105
	s_waitcnt lgkmcnt(10)
	v_mfma_f32_32x32x16_bf16 v[18:33], v[146:149], v[68:71], v[18:33]
	v_exp_f32_e32 v106, v106
	v_exp_f32_e32 v107, v107
	v_exp_f32_e32 v108, v108
	v_exp_f32_e32 v109, v109
	s_waitcnt lgkmcnt(8)
	v_mfma_f32_32x32x16_bf16 v[34:49], v[146:149], v[72:75], v[34:49]
	v_exp_f32_e32 v110, v110
	v_exp_f32_e32 v111, v111
	v_exp_f32_e32 v112, v112
	v_exp_f32_e32 v113, v113
	s_waitcnt vmcnt(2) lgkmcnt(0)
	s_barrier
	s_add_i32 s7, s25, 0x2000
	s_cmpk_lg_i32 s25, 0x4000
	s_cselect_b32 s24, s7, 0
	v_add_u32_e32 v64, s6, v243
	ds_read_b64_tr_b16 v[190:191], v64 offset:24576
	ds_read_b64_tr_b16 v[192:193], v64 offset:25088
	s_waitcnt lgkmcnt(9)
	v_mfma_f32_32x32x16_bf16 v[82:97], v[60:63], v[150:153], v[2:17]
	v_add_f32_e32 v65, v114, v115
	v_add_f32_e32 v65, v116, v65
	v_add_f32_e32 v65, v117, v65
	v_add_f32_e32 v65, v118, v65
	v_add_f32_e32 v65, v119, v65
	v_cvt_pk_bf16_f32 v162, v114, v115
	v_cvt_pk_bf16_f32 v163, v116, v117
	ds_read_b64_tr_b16 v[60:61], v64 offset:28672
	ds_read_b64_tr_b16 v[62:63], v64 offset:29184
	s_waitcnt lgkmcnt(10)
	v_mfma_f32_32x32x16_bf16 v[66:81], v[166:169], v[150:153], v[2:17]
	v_add_f32_e32 v65, v120, v65
	v_add_f32_e32 v65, v121, v65
	v_add_f32_e32 v65, v122, v65
	v_add_f32_e32 v65, v123, v65
	v_cvt_pk_bf16_f32 v164, v118, v119
	v_cvt_pk_bf16_f32 v165, v120, v121
	ds_read_b64_tr_b16 v[114:115], v64 offset:25600
	ds_read_b64_tr_b16 v[116:117], v64 offset:26112
	s_waitcnt lgkmcnt(11)
	v_mfma_f32_32x32x16_bf16 v[82:97], v[170:173], v[142:145], v[82:97]
	v_add_f32_e32 v65, v124, v65
	v_add_f32_e32 v65, v125, v65
	v_add_f32_e32 v65, v126, v65
	v_add_f32_e32 v65, v127, v65
	v_cvt_pk_bf16_f32 v158, v122, v123
	v_cvt_pk_bf16_f32 v159, v124, v125
	ds_read_b64_tr_b16 v[118:119], v64 offset:29696
	ds_read_b64_tr_b16 v[120:121], v64 offset:30208
	s_waitcnt lgkmcnt(12)
	v_mfma_f32_32x32x16_bf16 v[66:81], v[174:177], v[142:145], v[66:81]
	v_add_f32_e32 v65, v128, v65
	v_add_f32_e32 v65, v129, v65
	v_add_f32_e32 v65, v98, v65
	v_add_f32_e32 v65, v99, v65
	v_cvt_pk_bf16_f32 v160, v126, v127
	v_cvt_pk_bf16_f32 v161, v128, v129
	ds_read_b64_tr_b16 v[122:123], v64 offset:26624
	ds_read_b64_tr_b16 v[124:125], v64 offset:27136
	s_waitcnt lgkmcnt(13)
	v_mfma_f32_32x32x16_bf16 v[82:97], v[178:181], v[138:141], v[82:97]
	v_add_f32_e32 v65, v100, v65
	v_add_f32_e32 v65, v101, v65
	v_add_f32_e32 v65, v102, v65
	v_add_f32_e32 v65, v103, v65
	v_cvt_pk_bf16_f32 v154, v98, v99
	v_cvt_pk_bf16_f32 v155, v100, v101
	ds_read_b64_tr_b16 v[98:99], v64 offset:30720
	ds_read_b64_tr_b16 v[100:101], v64 offset:31232
	s_waitcnt lgkmcnt(14)
	v_mfma_f32_32x32x16_bf16 v[66:81], v[182:185], v[138:141], v[66:81]
	v_add_f32_e32 v65, v104, v65
	v_add_f32_e32 v65, v105, v65
	v_add_f32_e32 v65, v106, v65
	v_add_f32_e32 v65, v107, v65
	v_cvt_pk_bf16_f32 v156, v102, v103
	v_cvt_pk_bf16_f32 v157, v104, v105
	ds_read_b64_tr_b16 v[102:103], v64 offset:27648
	ds_read_b64_tr_b16 v[104:105], v64 offset:28160
	s_waitcnt lgkmcnt(14)
	v_mfma_f32_32x32x16_bf16 v[82:97], v[186:189], v[134:137], v[82:97]
	v_add_f32_e32 v65, v108, v65
	v_add_f32_e32 v65, v109, v65
	v_add_f32_e32 v65, v110, v65
	v_add_f32_e32 v65, v111, v65
	v_cvt_pk_bf16_f32 v146, v106, v107
	v_cvt_pk_bf16_f32 v147, v108, v109
	ds_read_b64_tr_b16 v[106:107], v64 offset:31744
	ds_read_b64_tr_b16 v[108:109], v64 offset:32256
	v_mfma_f32_32x32x16_bf16 v[66:81], v[52:55], v[134:137], v[66:81]
	v_add_f32_e32 v52, v112, v65
	v_add_f32_e32 v52, v113, v52
	v_add_f32_e32 v52, 0, v52
	v_cvt_pk_bf16_f32 v148, v110, v111
	v_cvt_pk_bf16_f32 v149, v112, v113
	s_add_i32 s6, s25, s22
	s_mov_b32 s7, m0
	s_mov_b32 m0, s6
	s_nop 0
	global_load_lds_dwordx4 v[58:59], off
	s_mov_b32 m0, s7
	s_add_i32 s6, s24, s23
	s_mov_b32 s7, m0
	s_mov_b32 m0, s6
	s_nop 0
	global_load_lds_dwordx4 v[56:57], off
	s_mov_b32 m0, s7
	s_waitcnt lgkmcnt(14)
	v_mfma_f32_32x32x16_bf16 v[18:33], v[162:165], v[190:193], v[18:33]
	v_exp_f32_e32 v82, v82
	v_exp_f32_e32 v83, v83
	v_exp_f32_e32 v84, v84
	v_exp_f32_e32 v85, v85
	s_waitcnt lgkmcnt(12)
	v_mfma_f32_32x32x16_bf16 v[34:49], v[162:165], v[60:63], v[34:49]
	v_exp_f32_e32 v86, v86
	v_exp_f32_e32 v87, v87
	v_exp_f32_e32 v88, v88
	v_exp_f32_e32 v89, v89
	v_add_u32_e32 v53, s24, v240
	ds_read_b128 v[194:197], v53
	ds_read_b128 v[190:193], v53 offset:512
	s_waitcnt lgkmcnt(12)
	v_mfma_f32_32x32x16_bf16 v[18:33], v[158:161], v[114:117], v[18:33]
	v_exp_f32_e32 v90, v90
	v_exp_f32_e32 v91, v91
	v_exp_f32_e32 v92, v92
	v_exp_f32_e32 v93, v93
	ds_read_b128 v[186:189], v53 offset:2048
	ds_read_b128 v[182:185], v53 offset:2560
	s_waitcnt lgkmcnt(12)
	v_mfma_f32_32x32x16_bf16 v[34:49], v[158:161], v[118:121], v[34:49]
	v_exp_f32_e32 v94, v94
	v_exp_f32_e32 v95, v95
	v_exp_f32_e32 v96, v96
	v_exp_f32_e32 v97, v97
	ds_read_b128 v[178:181], v53 offset:4096
	ds_read_b128 v[174:177], v53 offset:4608
	s_waitcnt lgkmcnt(12)
	v_mfma_f32_32x32x16_bf16 v[18:33], v[154:157], v[122:125], v[18:33]
	v_exp_f32_e32 v66, v66
	v_exp_f32_e32 v67, v67
	v_exp_f32_e32 v68, v68
	v_exp_f32_e32 v69, v69
	ds_read_b128 v[170:173], v53 offset:6144
	ds_read_b128 v[166:169], v53 offset:6656
	s_waitcnt lgkmcnt(12)
	v_mfma_f32_32x32x16_bf16 v[34:49], v[154:157], v[98:101], v[34:49]
	v_exp_f32_e32 v70, v70
	v_exp_f32_e32 v71, v71
	v_exp_f32_e32 v72, v72
	v_exp_f32_e32 v73, v73
	s_waitcnt lgkmcnt(10)
	v_mfma_f32_32x32x16_bf16 v[18:33], v[146:149], v[102:105], v[18:33]
	v_exp_f32_e32 v74, v74
	v_exp_f32_e32 v75, v75
	v_exp_f32_e32 v76, v76
	v_exp_f32_e32 v77, v77
	s_waitcnt lgkmcnt(8)
	v_mfma_f32_32x32x16_bf16 v[34:49], v[146:149], v[106:109], v[34:49]
	v_exp_f32_e32 v78, v78
	v_exp_f32_e32 v79, v79
	v_exp_f32_e32 v80, v80
	v_exp_f32_e32 v81, v81
	s_add_i32 s6, s24, 0x2000
	s_waitcnt vmcnt(2) lgkmcnt(0)
	s_barrier
	s_cmpk_lg_i32 s24, 0x4000
	v_add_f32_e32 v50, v50, v51
	s_mov_b32 s18, s25
	s_cselect_b32 s25, s6, 0
	s_add_i32 s7, s1, 2
	v_lshl_add_u64 v[56:57], v[56:57], 0, s[90:91]
	v_lshl_add_u64 v[58:59], v[58:59], 0, s[90:91]
	s_cmp_ge_u32 s7, s38
	v_add_f32_e32 v50, v50, v52
	s_cbranch_scc0 .LBB0_923
	s_add_i32 s80, s1, -3
	s_add_i32 s1, s80, 1
	s_cmp_ge_u32 s1, s38
	s_cbranch_scc0 .LBB0_929

.LBB0_966:
	v_readlane_b32 s0, v255, 13
	v_readlane_b32 s1, v255, 14
	s_and_b64 s[0:1], s[0:1], exec
	s_movk_i32 s0, 0x4200
	s_cselect_b32 s2, 0x4000, s0
	s_lshr_b32 s8, s2, 5
	s_ashr_i32 s3, s3, 6
	v_readlane_b32 s0, v254, 46
	s_cmp_ge_i32 s0, s8
	s_barrier
	s_cbranch_scc1 .LBB0_969
	v_lshrrev_b32_e32 v5, 4, v233
	v_lshlrev_b32_e32 v0, 4, v234
	s_add_u32 s0, s10, 0x9900000
	v_readlane_b32 s4, v255, 8
	v_ashrrev_i32_e32 v36, 2, v234
	v_and_b32_e32 v2, 48, v0
	v_lshlrev_b32_e32 v0, 5, v5
	s_movk_i32 s6, 0x90
	s_addc_u32 s1, s11, 0
	s_lshl_b32 s9, s4, 9
	v_and_b32_e32 v3, 15, v234
	v_lshl_add_u64 v[20:21], v[130:131], 0, v[0:1]
	v_mul_lo_u32 v0, v36, s6
	v_lshlrev_b32_e32 v6, 1, v2
	s_add_u32 s4, s10, 0x90c0000
	v_lshl_or_b32 v18, s3, 4, v3
	v_lshlrev_b32_e32 v4, 2, v5
	v_add3_u32 v37, 0, v0, v6
	v_lshlrev_b32_e32 v0, 1, v3
	v_mul_u32_u24_e32 v3, 0x480, v5
	s_addc_u32 s5, s11, 0
	v_ashrrev_i32_e32 v19, 31, v18
	v_add3_u32 v38, 0, v0, v3
	v_lshlrev_b32_e32 v0, 1, v2
	v_lshlrev_b32_e32 v22, 1, v4
	v_readlane_b32 s14, v254, 50
	v_readlane_b32 s15, v254, 46
	s_mov_b32 s100, s42
	s_mov_b32 s101, s79
	s_cmpk_eq_i32 s8, 0x210
	s_cbranch_scc0 .Lgm_keep
	s_cmp_lt_u32 s72, 16
	s_cbranch_scc1 .LBB0_969
	s_sub_i32 s15, s72, 16
	s_lshl_b32 s14, s15, 5
	s_movk_i32 s100, 0xf0
	s_movk_i32 s101, 0x1e00
.Lgm_keep:
.LBB0_968:
	s_lshl_b32 s6, s15, 7
	s_and_b32 s6, s6, 0x180
	s_or_b32 s80, s6, s9
	s_and_b32 s16, s14, 0xffffff80
	v_lshl_add_u64 v[2:3], s[80:81], 0, v[18:19]
	v_lshlrev_b64 v[10:11], 9, v[2:3]
	v_add_u32_e32 v2, s16, v36
	v_ashrrev_i32_e32 v3, 31, v2
	v_lshlrev_b64 v[2:3], 9, v[2:3]
	v_lshl_add_u64 v[2:3], s[0:1], 0, v[2:3]
	s_mov_b32 s7, s81
	v_lshl_add_u64 v[2:3], v[2:3], 0, s[6:7]
	v_lshl_add_u64 v[6:7], v[2:3], 0, v[0:1]
	v_lshl_add_u64 v[24:25], v[20:21], 0, v[10:11]
	global_load_dwordx4 v[2:5], v[6:7], off offset:16
	s_nop 0
	global_load_dwordx4 v[6:9], v[6:7], off
	s_nop 0
	global_load_dwordx4 v[10:13], v[24:25], off offset:16
	global_load_dwordx4 v[14:17], v[24:25], off
	global_load_dwordx4 v[30:33], v[24:25], off offset:144
	global_load_dwordx4 v[40:43], v[24:25], off offset:128
	global_load_dwordx4 v[44:47], v[24:25], off offset:272
	global_load_dwordx4 v[48:51], v[24:25], off offset:256
	global_load_dwordx4 v[52:55], v[24:25], off offset:400
	global_load_dwordx4 v[56:59], v[24:25], off offset:384
	v_add_u32_e32 v24, s80, v18
	v_ashrrev_i32_e32 v25, 31, v24
	v_add_u32_e32 v34, s16, v18
	v_lshl_add_u64 v[24:25], v[24:25], 2, v[132:133]
	v_ashrrev_i32_e32 v35, 31, v34
	global_load_dword v39, v[24:25], off
	v_lshlrev_b64 v[24:25], 9, v[34:35]
	v_lshl_add_u64 v[24:25], s[4:5], 0, v[24:25]
	v_lshl_add_u64 v[24:25], v[24:25], 0, s[6:7]
	v_mov_b32_e32 v23, v1
	v_lshl_add_u64 v[24:25], v[24:25], 0, v[22:23]
	global_load_dwordx2 v[60:61], v[24:25], off
	global_load_dwordx2 v[28:29], v[24:25], off offset:32
	global_load_dwordx2 v[26:27], v[24:25], off offset:64
	s_nop 0
	global_load_dwordx2 v[24:25], v[24:25], off offset:96
	s_add_i32 s15, s15, s100
	s_add_i32 s14, s14, s101
	s_cmp_ge_i32 s15, s8
	s_waitcnt vmcnt(13)
	ds_write_b128 v37, v[6:9]
	ds_write_b128 v37, v[2:5] offset:16
	s_waitcnt lgkmcnt(0)
	s_barrier
	s_waitcnt vmcnt(11)
	v_cvt_pk_bf16_f32 v14, v14, v15
	v_cvt_pk_bf16_f32 v15, v16, v17
	v_cvt_pk_bf16_f32 v16, v10, v11
	v_cvt_pk_bf16_f32 v17, v12, v13
	s_waitcnt vmcnt(9)
	v_cvt_pk_bf16_f32 v10, v40, v41
	v_cvt_pk_bf16_f32 v11, v42, v43
	v_cvt_pk_bf16_f32 v12, v30, v31
	v_cvt_pk_bf16_f32 v13, v32, v33
	s_waitcnt vmcnt(7)
	v_cvt_pk_bf16_f32 v6, v48, v49
	v_cvt_pk_bf16_f32 v7, v50, v51
	v_cvt_pk_bf16_f32 v8, v44, v45
	v_cvt_pk_bf16_f32 v9, v46, v47
	s_waitcnt vmcnt(5)
	v_cvt_pk_bf16_f32 v2, v56, v57
	v_cvt_pk_bf16_f32 v3, v58, v59
	v_cvt_pk_bf16_f32 v4, v52, v53
	v_cvt_pk_bf16_f32 v5, v54, v55
	v_lshlrev_b64 v[30:31], 11, v[34:35]
	ds_read_u16 v23, v38
	ds_read_u16 v32, v38 offset:144
	ds_read_u16 v33, v38 offset:288
	ds_read_u16 v40, v38 offset:432
	ds_read_u16 v34, v38 offset:576
	ds_read_u16 v41, v38 offset:720
	ds_read_u16 v35, v38 offset:864
	ds_read_u16 v42, v38 offset:1008
	s_waitcnt lgkmcnt(4)
	v_perm_b32 v33, v40, v33, s49
	v_perm_b32 v32, v32, v23, s49
	s_waitcnt lgkmcnt(2)
	v_perm_b32 v34, v41, v34, s49
	v_lshl_add_u64 v[30:31], s[12:13], 0, v[30:31]
	s_waitcnt lgkmcnt(0)
	v_perm_b32 v35, v42, v35, s49
	ds_read_u16 v23, v38 offset:4608
	ds_read_u16 v40, v38 offset:4752
	ds_read_u16 v41, v38 offset:4896
	ds_read_u16 v44, v38 offset:5040
	ds_read_u16 v42, v38 offset:5184
	ds_read_u16 v45, v38 offset:5328
	ds_read_u16 v43, v38 offset:5472
	ds_read_u16 v46, v38 offset:5616
	s_waitcnt lgkmcnt(4)
	v_perm_b32 v41, v44, v41, s49
	v_perm_b32 v40, v40, v23, s49
	s_waitcnt lgkmcnt(2)
	v_perm_b32 v42, v45, v42, s49
	v_mfma_f32_16x16x32_bf16 v[32:35], v[32:35], v[14:17], 0
	s_waitcnt lgkmcnt(0)
	v_perm_b32 v43, v46, v43, s49
	s_nop 1
	v_mfma_f32_16x16x32_bf16 v[32:35], v[40:43], v[10:13], v[32:35]
	ds_read_u16 v23, v38 offset:9216
	ds_read_u16 v40, v38 offset:9360
	ds_read_u16 v41, v38 offset:9504
	ds_read_u16 v44, v38 offset:9648
	ds_read_u16 v42, v38 offset:9792
	ds_read_u16 v45, v38 offset:9936
	ds_read_u16 v43, v38 offset:10080
	ds_read_u16 v46, v38 offset:10224
	s_waitcnt lgkmcnt(4)
	v_perm_b32 v41, v44, v41, s49
	v_perm_b32 v40, v40, v23, s49
	s_waitcnt lgkmcnt(2)
	v_perm_b32 v42, v45, v42, s49
	s_waitcnt lgkmcnt(0)
	v_perm_b32 v43, v46, v43, s49
	s_nop 1
	v_mfma_f32_16x16x32_bf16 v[32:35], v[40:43], v[6:9], v[32:35]
	ds_read_u16 v23, v38 offset:13824
	ds_read_u16 v40, v38 offset:13968
	ds_read_u16 v41, v38 offset:14112
	ds_read_u16 v44, v38 offset:14256
	ds_read_u16 v42, v38 offset:14400
	ds_read_u16 v45, v38 offset:14544
	ds_read_u16 v43, v38 offset:14688
	ds_read_u16 v46, v38 offset:14832
	s_waitcnt lgkmcnt(4)
	v_perm_b32 v41, v44, v41, s49
	v_perm_b32 v40, v40, v23, s49
	s_waitcnt lgkmcnt(2)
	v_perm_b32 v42, v45, v42, s49
	s_waitcnt vmcnt(3)
	v_lshlrev_b32_e32 v23, 16, v60
	s_waitcnt lgkmcnt(0)
	v_perm_b32 v43, v46, v43, s49
	s_nop 1
	v_mfma_f32_16x16x32_bf16 v[32:35], v[40:43], v[2:5], v[32:35]
	s_nop 7
	v_add_f32_e32 v32, v39, v32
	v_mul_f32_e32 v23, v32, v23
	v_and_b32_e32 v32, 0xffff0000, v60
	v_add_f32_e32 v33, v39, v33
	v_mul_f32_e32 v32, v33, v32
	v_cvt_pk_bf16_f32 v32, v23, v32
	v_lshlrev_b32_e32 v23, 16, v61
	v_add_f32_e32 v33, v39, v34
	v_mul_f32_e32 v23, v33, v23
	v_and_b32_e32 v33, 0xffff0000, v61
	v_add_f32_e32 v34, v39, v35
	v_mul_f32_e32 v33, v34, v33
	v_or_b32_e32 v34, s6, v22
	v_mov_b32_e32 v35, v1
	v_lshl_add_u64 v[44:45], v[30:31], 0, v[34:35]
	v_cvt_pk_bf16_f32 v33, v23, v33
	global_store_dwordx2 v[44:45], v[32:33], off
	ds_read_u16 v23, v38 offset:32
	ds_read_u16 v30, v38 offset:176
	ds_read_u16 v31, v38 offset:320
	ds_read_u16 v34, v38 offset:464
	ds_read_u16 v32, v38 offset:608
	ds_read_u16 v35, v38 offset:752
	ds_read_u16 v33, v38 offset:896
	ds_read_u16 v40, v38 offset:1040
	s_waitcnt lgkmcnt(4)
	v_perm_b32 v31, v34, v31, s49
	v_perm_b32 v30, v30, v23, s49
	s_waitcnt lgkmcnt(2)
	v_perm_b32 v32, v35, v32, s49
	s_waitcnt lgkmcnt(0)
	v_perm_b32 v33, v40, v33, s49
	ds_read_u16 v23, v38 offset:4640
	ds_read_u16 v34, v38 offset:4784
	ds_read_u16 v35, v38 offset:4928
	ds_read_u16 v40, v38 offset:5072
	ds_read_u16 v41, v38 offset:5216
	ds_read_u16 v42, v38 offset:5360
	ds_read_u16 v43, v38 offset:5504
	ds_read_u16 v46, v38 offset:5648
	v_mfma_f32_16x16x32_bf16 v[30:33], v[30:33], v[14:17], 0
	s_waitcnt lgkmcnt(0)
	v_perm_b32 v43, v46, v43, s49
	v_perm_b32 v42, v42, v41, s49
	v_perm_b32 v41, v40, v35, s49
	v_perm_b32 v40, v34, v23, s49
	s_nop 1
	v_mfma_f32_16x16x32_bf16 v[30:33], v[40:43], v[10:13], v[30:33]
	ds_read_u16 v23, v38 offset:9248
	ds_read_u16 v34, v38 offset:9392
	ds_read_u16 v35, v38 offset:9536
	ds_read_u16 v40, v38 offset:9680
	ds_read_u16 v41, v38 offset:9824
	ds_read_u16 v42, v38 offset:9968
	ds_read_u16 v43, v38 offset:10112
	ds_read_u16 v46, v38 offset:10256
	s_waitcnt lgkmcnt(2)
	v_perm_b32 v42, v42, v41, s49
	v_perm_b32 v41, v40, v35, s49
	s_waitcnt lgkmcnt(0)
	v_perm_b32 v43, v46, v43, s49
	v_perm_b32 v40, v34, v23, s49
	s_nop 1
	v_mfma_f32_16x16x32_bf16 v[30:33], v[40:43], v[6:9], v[30:33]
	ds_read_u16 v23, v38 offset:13856
	ds_read_u16 v34, v38 offset:14000
	ds_read_u16 v35, v38 offset:14144
	ds_read_u16 v40, v38 offset:14288
	ds_read_u16 v41, v38 offset:14432
	ds_read_u16 v42, v38 offset:14576
	ds_read_u16 v43, v38 offset:14720
	ds_read_u16 v46, v38 offset:14864
	s_waitcnt lgkmcnt(2)
	v_perm_b32 v42, v42, v41, s49
	v_perm_b32 v41, v40, v35, s49
	s_waitcnt lgkmcnt(0)
	v_perm_b32 v43, v46, v43, s49
	v_perm_b32 v40, v34, v23, s49
	s_waitcnt vmcnt(3)
	v_lshlrev_b32_e32 v23, 16, v28
	v_and_b32_e32 v28, 0xffff0000, v28
	v_mfma_f32_16x16x32_bf16 v[30:33], v[40:43], v[2:5], v[30:33]
	s_nop 7
	v_add_f32_e32 v30, v39, v30
	v_mul_f32_e32 v23, v30, v23
	v_add_f32_e32 v30, v39, v31
	v_mul_f32_e32 v28, v30, v28
	v_cvt_pk_bf16_f32 v28, v23, v28
	v_lshlrev_b32_e32 v23, 16, v29
	v_add_f32_e32 v30, v39, v32
	v_mul_f32_e32 v23, v30, v23
	v_and_b32_e32 v29, 0xffff0000, v29
	v_add_f32_e32 v30, v39, v33
	v_mul_f32_e32 v29, v30, v29
	v_cvt_pk_bf16_f32 v29, v23, v29
	global_store_dwordx2 v[44:45], v[28:29], off offset:32
	ds_read_u16 v23, v38 offset:64
	ds_read_u16 v28, v38 offset:208
	ds_read_u16 v29, v38 offset:352
	ds_read_u16 v32, v38 offset:496
	ds_read_u16 v30, v38 offset:640
	ds_read_u16 v33, v38 offset:784
	ds_read_u16 v31, v38 offset:928
	ds_read_u16 v34, v38 offset:1072
	s_waitcnt lgkmcnt(4)
	v_perm_b32 v29, v32, v29, s49
	v_perm_b32 v28, v28, v23, s49
	s_waitcnt lgkmcnt(2)
	v_perm_b32 v30, v33, v30, s49
	s_waitcnt lgkmcnt(0)
	v_perm_b32 v31, v34, v31, s49
	ds_read_u16 v23, v38 offset:4672
	ds_read_u16 v32, v38 offset:4816
	ds_read_u16 v33, v38 offset:4960
	ds_read_u16 v40, v38 offset:5104
	ds_read_u16 v34, v38 offset:5248
	ds_read_u16 v41, v38 offset:5392
	ds_read_u16 v35, v38 offset:5536
	ds_read_u16 v42, v38 offset:5680
	s_waitcnt lgkmcnt(4)
	v_perm_b32 v33, v40, v33, s49
	v_perm_b32 v32, v32, v23, s49
	s_waitcnt lgkmcnt(2)
	v_perm_b32 v34, v41, v34, s49
	v_mfma_f32_16x16x32_bf16 v[28:31], v[28:31], v[14:17], 0
	s_waitcnt lgkmcnt(0)
	v_perm_b32 v35, v42, v35, s49
	s_nop 1
	v_mfma_f32_16x16x32_bf16 v[28:31], v[32:35], v[10:13], v[28:31]
	ds_read_u16 v23, v38 offset:9280
	ds_read_u16 v32, v38 offset:9424
	ds_read_u16 v33, v38 offset:9568
	ds_read_u16 v40, v38 offset:9712
	ds_read_u16 v34, v38 offset:9856
	ds_read_u16 v41, v38 offset:10000
	ds_read_u16 v35, v38 offset:10144
	ds_read_u16 v42, v38 offset:10288
	s_waitcnt lgkmcnt(4)
	v_perm_b32 v33, v40, v33, s49
	v_perm_b32 v32, v32, v23, s49
	s_waitcnt lgkmcnt(2)
	v_perm_b32 v34, v41, v34, s49
	s_waitcnt lgkmcnt(0)
	v_perm_b32 v35, v42, v35, s49
	s_nop 1
	v_mfma_f32_16x16x32_bf16 v[28:31], v[32:35], v[6:9], v[28:31]
	ds_read_u16 v23, v38 offset:13888
	ds_read_u16 v32, v38 offset:14032
	ds_read_u16 v33, v38 offset:14176
	ds_read_u16 v40, v38 offset:14320
	ds_read_u16 v34, v38 offset:14464
	ds_read_u16 v41, v38 offset:14608
	ds_read_u16 v35, v38 offset:14752
	ds_read_u16 v42, v38 offset:14896
	s_waitcnt lgkmcnt(4)
	v_perm_b32 v33, v40, v33, s49
	v_perm_b32 v32, v32, v23, s49
	s_waitcnt lgkmcnt(2)
	v_perm_b32 v34, v41, v34, s49
	s_waitcnt vmcnt(3)
	v_lshlrev_b32_e32 v23, 16, v26
	s_waitcnt lgkmcnt(0)
	v_perm_b32 v35, v42, v35, s49
	v_and_b32_e32 v26, 0xffff0000, v26
	s_nop 0
	v_mfma_f32_16x16x32_bf16 v[28:31], v[32:35], v[2:5], v[28:31]
	s_nop 7
	v_add_f32_e32 v28, v39, v28
	v_mul_f32_e32 v23, v28, v23
	v_add_f32_e32 v28, v39, v29
	v_mul_f32_e32 v26, v28, v26
	v_cvt_pk_bf16_f32 v26, v23, v26
	v_lshlrev_b32_e32 v23, 16, v27
	v_add_f32_e32 v28, v39, v30
	v_mul_f32_e32 v23, v28, v23
	v_and_b32_e32 v27, 0xffff0000, v27
	v_add_f32_e32 v28, v39, v31
	v_mul_f32_e32 v27, v28, v27
	v_cvt_pk_bf16_f32 v27, v23, v27
	global_store_dwordx2 v[44:45], v[26:27], off offset:64
	ds_read_u16 v23, v38 offset:96
	ds_read_u16 v26, v38 offset:240
	ds_read_u16 v27, v38 offset:384
	ds_read_u16 v30, v38 offset:528
	ds_read_u16 v28, v38 offset:672
	ds_read_u16 v31, v38 offset:816
	ds_read_u16 v29, v38 offset:960
	ds_read_u16 v32, v38 offset:1104
	s_waitcnt lgkmcnt(4)
	v_perm_b32 v27, v30, v27, s49
	v_perm_b32 v26, v26, v23, s49
	s_waitcnt lgkmcnt(2)
	v_perm_b32 v28, v31, v28, s49
	s_waitcnt lgkmcnt(0)
	v_perm_b32 v29, v32, v29, s49
	s_nop 1
	v_mfma_f32_16x16x32_bf16 v[14:17], v[26:29], v[14:17], 0
	ds_read_u16 v23, v38 offset:4704
	ds_read_u16 v26, v38 offset:4848
	ds_read_u16 v27, v38 offset:4992
	ds_read_u16 v30, v38 offset:5136
	ds_read_u16 v28, v38 offset:5280
	ds_read_u16 v31, v38 offset:5424
	ds_read_u16 v29, v38 offset:5568
	ds_read_u16 v32, v38 offset:5712
	s_waitcnt lgkmcnt(4)
	v_perm_b32 v27, v30, v27, s49
	v_perm_b32 v26, v26, v23, s49
	s_waitcnt lgkmcnt(2)
	v_perm_b32 v28, v31, v28, s49
	s_waitcnt lgkmcnt(0)
	v_perm_b32 v29, v32, v29, s49
	s_nop 1
	v_mfma_f32_16x16x32_bf16 v[10:13], v[26:29], v[10:13], v[14:17]
	s_nop 2
	ds_read_u16 v14, v38 offset:9312
	ds_read_u16 v23, v38 offset:9456
	ds_read_u16 v15, v38 offset:9600
	ds_read_u16 v26, v38 offset:9744
	ds_read_u16 v16, v38 offset:9888
	ds_read_u16 v27, v38 offset:10032
	ds_read_u16 v17, v38 offset:10176
	ds_read_u16 v28, v38 offset:10320
	s_waitcnt lgkmcnt(4)
	v_perm_b32 v15, v26, v15, s49
	v_perm_b32 v14, v23, v14, s49
	s_waitcnt lgkmcnt(2)
	v_perm_b32 v16, v27, v16, s49
	s_waitcnt lgkmcnt(0)
	v_perm_b32 v17, v28, v17, s49
	s_nop 1
	v_mfma_f32_16x16x32_bf16 v[6:9], v[14:17], v[6:9], v[10:13]
	s_nop 2
	ds_read_u16 v10, v38 offset:13920
	ds_read_u16 v14, v38 offset:14064
	ds_read_u16 v11, v38 offset:14208
	ds_read_u16 v15, v38 offset:14352
	ds_read_u16 v12, v38 offset:14496
	ds_read_u16 v16, v38 offset:14640
	ds_read_u16 v13, v38 offset:14784
	ds_read_u16 v17, v38 offset:14928
	s_waitcnt lgkmcnt(4)
	v_perm_b32 v11, v15, v11, s49
	v_perm_b32 v10, v14, v10, s49
	s_waitcnt lgkmcnt(2)
	v_perm_b32 v12, v16, v12, s49
	s_waitcnt lgkmcnt(0)
	v_perm_b32 v13, v17, v13, s49
	s_nop 1
	v_mfma_f32_16x16x32_bf16 v[2:5], v[10:13], v[2:5], v[6:9]
	s_waitcnt vmcnt(3)
	s_nop 1
	v_lshlrev_b32_e32 v6, 16, v24
	s_nop 3
	v_add_f32_e32 v2, v39, v2
	v_mul_f32_e32 v2, v2, v6
	v_and_b32_e32 v6, 0xffff0000, v24
	v_add_f32_e32 v3, v39, v3
	v_mul_f32_e32 v3, v3, v6
	v_cvt_pk_bf16_f32 v2, v2, v3
	v_lshlrev_b32_e32 v3, 16, v25
	v_add_f32_e32 v4, v39, v4
	v_mul_f32_e32 v3, v4, v3
	v_and_b32_e32 v4, 0xffff0000, v25
	v_add_f32_e32 v5, v39, v5
	v_mul_f32_e32 v4, v5, v4
	v_cvt_pk_bf16_f32 v3, v3, v4
	global_store_dwordx2 v[44:45], v[2:3], off offset:96
	s_barrier
	s_cbranch_scc0 .LBB0_968
